# XCD-local grid barriers at 4 seams (GEMM1->conv/KV, Qup->attn, attn->merge, merge->out): skip cross-XCD level and L2 writeback when WG->XCC mapping is the natural one (runtime-checked, falls back to g
# speedup vs baseline: 1.0071x; 1.0027x over previous
; #define LAS __attribute__((address_space(3)))
; __device__ __forceinline__ unsigned xb_add(unsigned* p, unsigned v) { return __hip_atomic_fetch_add(p, v, __ATOMIC_RELAXED, __HIP_MEMORY_SCOPE_AGENT); }
; __device__ __forceinline__ unsigned xb_xcc_id() { return (unsigned)__builtin_amdgcn_s_getreg((3 << 11) | 20) & 0xFu; }
; __device__ __forceinline__ XcdBarrier xcd_barrier_post(unsigned* bar, volatile LAS unsigned* st) {
;     XcdBarrier b; b.bar = bar; b.x = xb_xcc_id(); b.st = st;
;     if (threadIdx.x == 0) (void)xb_add(&bar[XB_XCNT(b.x)], 1u);
;     return b;
; }
; __global__ void __launch_bounds__(512, 2) fwd_kernel(Args a) {
;     ...
;     volatile LAS unsigned* bst = (volatile LAS unsigned*)(lds + 147456 + 64);
;     if (threadIdx.x < 2) bst[threadIdx.x] = 0u;
;     __syncthreads();
;     XcdBarrier bar = xcd_barrier_post((unsigned*)(P.ws + WS_BAR), bst);
.LBB0_2:
	s_load_dwordx2 s[92:93], s[0:1], 0x90
	s_load_dwordx4 s[88:91], s[0:1], 0x80
	v_and_b32_e32 v200, 0x3ff, v0
	v_cmp_gt_u32_e32 vcc, 2, v200
	s_and_saveexec_b64 s[2:3], vcc
	v_lshl_add_u32 v1, v200, 2, 0
	v_add_u32_e32 v1, 0x24040, v1
	v_mov_b32_e32 v2, 0
	ds_write_b32 v1, v2
	s_or_b64 exec, exec, s[2:3]
	s_waitcnt lgkmcnt(0)
	s_add_u32 s2, s90, 0x70000
	s_addc_u32 s3, s91, 0
	v_writelane_b32 v254, s2, 2
	s_barrier
	s_nop 0
	v_writelane_b32 v254, s3, 3
	s_getreg_b32 s2, hwreg(HW_REG_XCC_ID, 0, 4)
	s_and_b32 s2, s2, 15
	v_writelane_b32 v254, s2, 4
	v_cmp_eq_u32_e64 s[4:5], 0, v200
	s_mov_b64 s[2:3], exec
	s_nop 0
	v_writelane_b32 v254, s4, 5
	s_nop 1
	v_writelane_b32 v254, s5, 6
	s_and_b64 s[4:5], s[2:3], s[4:5]
	s_mov_b64 exec, s[4:5]
	s_cbranch_execz .LBB0_7
	s_mov_b64 s[4:5], exec
	v_mbcnt_lo_u32_b32 v1, s4, 0
	v_mbcnt_hi_u32_b32 v1, s5, v1
	v_cmp_eq_u32_e32 vcc, 0, v1
	s_and_b64 s[6:7], exec, vcc
	s_mov_b64 exec, s[6:7]
	s_cbranch_execz .LBB0_7
	v_readlane_b32 s6, v254, 4
	s_bcnt1_i32_b64 s4, s[4:5]
	s_lshl_b32 s6, s6, 8
	v_mov_b32_e32 v2, s4
	v_readlane_b32 s4, v254, 2
	v_mov_b32_e32 v1, s6
	v_readlane_b32 s5, v254, 3
	s_nop 4
	global_atomic_add v1, v2, s[4:5] offset:1024
	s_lshr_b32 s6, s6, 8
	s_and_b32 s7, s80, 7
	s_cmp_lg_u32 s6, s7
	s_cselect_b32 s6, 1, 0
	s_cmp_lg_u32 s83, 0x100
	s_cselect_b32 s7, 1, 0
	s_or_b32 s6, s6, s7
	s_cmp_eq_u32 s6, 0
	s_cbranch_scc1 .LBB0_7
	v_mov_b32_e32 v3, 0x3800
	global_atomic_add v3, v2, s[4:5]

; __device__ __forceinline__ unsigned xb_add(unsigned* p, unsigned v) { return __hip_atomic_fetch_add(p, v, __ATOMIC_RELAXED, __HIP_MEMORY_SCOPE_AGENT); }
; __device__ __forceinline__ void xcd_barrier(const XcdBarrier& b) {
;     asm volatile("s_waitcnt vmcnt(0)" ::: "memory");
;     __syncthreads();
;     if (threadIdx.x == 0) {
;         unsigned* bar = b.bar;
;         __builtin_amdgcn_s_waitcnt(0);
;         unsigned nloc = b.st[0], nx = b.st[1];
;         if (nloc == 0u) { xcd_barrier_complete(bar, b.x, nloc, nx); b.st[0] = nloc; b.st[1] = nx; }
;         const unsigned old = xb_add(&bar[XB_XSUB(b.x)], 1u);
;         const unsigned gen = old / nloc;
;         if (old + 1u == (gen + 1u) * nloc) {
;             __builtin_amdgcn_fence(__ATOMIC_RELEASE, "agent");
;             asm volatile("s_waitcnt vmcnt(0)" ::: "memory");
;             const unsigned og = xb_add(&bar[XB_TOP], 1u);
;             const unsigned tg = og / nx;
;             if (og + 1u == (tg + 1u) * nx) xb_add(&bar[XB_TOPGEN], 1u);
.LBB0_651:
	v_mov_b32_e32 v5, 0x73800
	global_load_dword v5, v5, s[90:91] sc1
	s_mov_b64 s[4:5], exec
	v_readlane_b32 s2, v254, 4
	s_lshl_b32 s2, s2, 8
	v_readlane_b32 s6, v254, 2
	v_mbcnt_lo_u32_b32 v1, s4, 0
	v_readlane_b32 s7, v254, 3
	s_add_u32 s2, s6, s2
	v_mbcnt_hi_u32_b32 v1, s5, v1
	s_addc_u32 s3, s7, 0
	v_cmp_eq_u32_e32 vcc, 0, v1
	s_and_saveexec_b64 s[6:7], vcc
	s_cbranch_execz .LBB0_653
	s_bcnt1_i32_b64 s4, s[4:5]
	v_mov_b32_e32 v3, 0x1000
	v_mov_b32_e32 v4, s4
	global_atomic_add v3, v3, v4, s[2:3] offset:1024 sc0
.LBB0_653:
	s_or_b64 exec, exec, s[6:7]
	v_cvt_f32_u32_e32 v4, v2
	s_waitcnt vmcnt(0)
	v_readfirstlane_b32 s4, v3
	v_readfirstlane_b32 s98, v5
	v_sub_u32_e32 v3, 0, v2
	v_rcp_iflag_f32_e32 v4, v4
	v_add_u32_e32 v5, s4, v1
	v_mul_f32_e32 v4, 0x4f7ffffe, v4
	v_cvt_u32_f32_e32 v4, v4
	v_mul_lo_u32 v1, v3, v4
	v_mul_hi_u32 v1, v4, v1
	v_add_u32_e32 v1, v4, v1
	v_mul_hi_u32 v1, v5, v1
	v_mul_lo_u32 v3, v1, v2
	v_sub_u32_e32 v3, v5, v3
	v_add_u32_e32 v4, 1, v1
	v_cmp_ge_u32_e32 vcc, v3, v2
	s_nop 1
	v_cndmask_b32_e32 v1, v1, v4, vcc
	v_sub_u32_e32 v4, v3, v2
	v_cndmask_b32_e32 v3, v3, v4, vcc
	v_add_u32_e32 v4, 1, v1
	v_cmp_ge_u32_e32 vcc, v3, v2
	v_add_u32_e32 v3, 1, v5
	s_nop 0
	v_cndmask_b32_e32 v1, v1, v4, vcc
	v_mul_lo_u32 v4, v2, v1
	v_add_u32_e32 v2, v4, v2
	v_cmp_ne_u32_e32 vcc, v3, v2
	s_and_saveexec_b64 s[4:5], vcc
	s_xor_b64 s[4:5], exec, s[4:5]
	s_cbranch_execz .LBB0_667
	s_waitcnt lgkmcnt(0)
	v_mov_b32_e32 v0, 0x2000
	global_load_dword v0, v0, s[2:3] offset:1024 sc1
	s_add_u32 s12, s2, 0x2400
	s_addc_u32 s13, s3, 0
	s_waitcnt vmcnt(0)
	v_cmp_eq_u32_e32 vcc, v0, v1
	s_and_saveexec_b64 s[6:7], vcc
	s_cbranch_execz .LBB0_666
	s_add_u32 s10, s90, 0x70200
	s_addc_u32 s11, s91, 0
	s_mov_b32 s24, 1
	s_mov_b64 s[14:15], 0
	v_mov_b32_e32 v0, 0
	s_branch .LBB0_657

; __device__ __forceinline__ unsigned xb_ld(unsigned* p)              { return __hip_atomic_load(p, __ATOMIC_RELAXED, __HIP_MEMORY_SCOPE_AGENT); }
; __device__ __forceinline__ unsigned xb_add(unsigned* p, unsigned v) { return __hip_atomic_fetch_add(p, v, __ATOMIC_RELAXED, __HIP_MEMORY_SCOPE_AGENT); }
; #define XB_SPIN(cond, bar) do { unsigned _sp = 0; while (cond) { __builtin_amdgcn_s_sleep(1); \
;     if ((++_sp & 255u) == 0u) { if (xb_ld(&(bar)[XB_TMO])) break; if (_sp > XB_SPIN_CAP) { atomicAdd(&(bar)[XB_TMO], 1u); break; } } } } while (0)
; __device__ __forceinline__ void xcd_barrier(const XcdBarrier& b) {
;     ...
;         if (old + 1u == (gen + 1u) * nloc) {
;             __builtin_amdgcn_fence(__ATOMIC_RELEASE, "agent");
;             asm volatile("s_waitcnt vmcnt(0)" ::: "memory");
;             const unsigned og = xb_add(&bar[XB_TOP], 1u);
;             const unsigned tg = og / nx;
;             if (og + 1u == (tg + 1u) * nx) xb_add(&bar[XB_TOPGEN], 1u);
;             else XB_SPIN(xb_ld(&bar[XB_TOPGEN]) == tg, bar);
;             __builtin_amdgcn_fence(__ATOMIC_ACQUIRE, "agent");
;             xb_add(&bar[XB_XGEN(b.x)], 1u);
.LBB0_667:
	s_andn2_saveexec_b64 s[4:5], s[4:5]
	s_cbranch_execz .LBB0_687
	s_waitcnt lgkmcnt(0)
	s_cmp_eq_u32 s98, 0
	s_cbranch_scc1 .Lxloc_2
	s_mov_b64 s[4:5], exec
	buffer_wbl2 sc1
	s_waitcnt lgkmcnt(0)
	s_waitcnt vmcnt(0)
	v_mbcnt_lo_u32_b32 v1, s4, 0
	v_mbcnt_hi_u32_b32 v1, s5, v1
	v_cmp_eq_u32_e32 vcc, 0, v1
	s_and_saveexec_b64 s[6:7], vcc
	s_cbranch_execz .LBB0_670
	s_bcnt1_i32_b64 s4, s[4:5]
	v_mov_b32_e32 v2, 0x73000
	v_mov_b32_e32 v3, s4
	global_atomic_add v2, v2, v3, s[90:91] offset:1024 sc0

; __device__ __forceinline__ unsigned xb_add(unsigned* p, unsigned v) { return __hip_atomic_fetch_add(p, v, __ATOMIC_RELAXED, __HIP_MEMORY_SCOPE_AGENT); }
; __device__ __forceinline__ void xcd_barrier(const XcdBarrier& b) {
;     ...
;             __builtin_amdgcn_fence(__ATOMIC_ACQUIRE, "agent");
;             xb_add(&bar[XB_XGEN(b.x)], 1u);
;             asm volatile("s_waitcnt vmcnt(0)" ::: "memory");
.Lxloc_2:
	s_mov_b64 s[4:5], exec
	v_mbcnt_lo_u32_b32 v0, s4, 0
	v_mbcnt_hi_u32_b32 v0, s5, v0
	v_cmp_eq_u32_e32 vcc, 0, v0
	s_waitcnt vmcnt(0)
	buffer_inv sc1
	s_and_saveexec_b64 s[6:7], vcc
	s_cbranch_execz .LBB0_686
	s_bcnt1_i32_b64 s4, s[4:5]
	v_mov_b32_e32 v0, 0x2000
	v_mov_b32_e32 v1, s4
	global_atomic_add v0, v1, s[2:3] offset:1024

; __device__ __forceinline__ unsigned xb_ld(unsigned* p)              { return __hip_atomic_load(p, __ATOMIC_RELAXED, __HIP_MEMORY_SCOPE_AGENT); }
; __device__ __forceinline__ unsigned xb_add(unsigned* p, unsigned v) { return __hip_atomic_fetch_add(p, v, __ATOMIC_RELAXED, __HIP_MEMORY_SCOPE_AGENT); }
; #define XB_SPIN(cond, bar) do { unsigned _sp = 0; while (cond) { __builtin_amdgcn_s_sleep(1); \
;     if ((++_sp & 255u) == 0u) { if (xb_ld(&(bar)[XB_TMO])) break; if (_sp > XB_SPIN_CAP) { atomicAdd(&(bar)[XB_TMO], 1u); break; } } } } while (0)
; __device__ __forceinline__ void xcd_barrier(const XcdBarrier& b) {
;     ...
;         const unsigned old = xb_add(&bar[XB_XSUB(b.x)], 1u);
;         const unsigned gen = old / nloc;
;         if (old + 1u == (gen + 1u) * nloc) {
;             __builtin_amdgcn_fence(__ATOMIC_RELEASE, "agent");
;             asm volatile("s_waitcnt vmcnt(0)" ::: "memory");
;             const unsigned og = xb_add(&bar[XB_TOP], 1u);
;             const unsigned tg = og / nx;
;             if (og + 1u == (tg + 1u) * nx) xb_add(&bar[XB_TOPGEN], 1u);
;             else XB_SPIN(xb_ld(&bar[XB_TOPGEN]) == tg, bar);
.LBB0_1090:
	s_andn2_saveexec_b64 s[6:7], s[6:7]
	s_cbranch_execz .LBB0_1110
	s_waitcnt lgkmcnt(0)
	s_cmp_eq_u32 s98, 0
	s_cbranch_scc1 .Lxloc_4
	s_mov_b64 s[6:7], exec
	buffer_wbl2 sc1
	s_waitcnt lgkmcnt(0)
	s_waitcnt vmcnt(0)
	v_mbcnt_lo_u32_b32 v1, s6, 0
	v_mbcnt_hi_u32_b32 v1, s7, v1
	v_cmp_eq_u32_e32 vcc, 0, v1
	s_and_saveexec_b64 s[8:9], vcc
	s_cbranch_execz .LBB0_1093
	s_bcnt1_i32_b64 s6, s[6:7]
	v_mov_b32_e32 v2, 0x73000
	v_mov_b32_e32 v3, s6
	global_atomic_add v2, v2, v3, s[90:91] offset:1024 sc0

; __device__ __forceinline__ unsigned xb_add(unsigned* p, unsigned v) { return __hip_atomic_fetch_add(p, v, __ATOMIC_RELAXED, __HIP_MEMORY_SCOPE_AGENT); }
; __device__ __forceinline__ void xcd_barrier(const XcdBarrier& b) {
;     ...
;             __builtin_amdgcn_fence(__ATOMIC_ACQUIRE, "agent");
;             xb_add(&bar[XB_XGEN(b.x)], 1u);
;             asm volatile("s_waitcnt vmcnt(0)" ::: "memory");
.Lxloc_4:
	s_mov_b64 s[6:7], exec
	v_mbcnt_lo_u32_b32 v0, s6, 0
	v_mbcnt_hi_u32_b32 v0, s7, v0
	v_cmp_eq_u32_e32 vcc, 0, v0
	s_waitcnt vmcnt(0)
	buffer_inv sc1
	s_and_saveexec_b64 s[8:9], vcc
	s_cbranch_execz .LBB0_1109
	s_bcnt1_i32_b64 s6, s[6:7]
	v_mov_b32_e32 v0, 0x2000
	v_mov_b32_e32 v1, s6
	global_atomic_add v0, v1, s[4:5] offset:1024
